# attention: window-mask VALU skipped on key tiles fully inside the window
# speedup vs baseline: 1.0334x; 1.0040x over previous
.LBB0_835:
	s_and_b32 s35, s30, 3
	s_lshl_b32 s31, s27, 7
	s_lshl_b32 s24, s35, 2
	s_add_i32 s41, s31, s29
	s_mov_b32 s100, s41
	s_or_b32 s30, s24, s28
	s_add_i32 s24, s41, s26
	s_ashr_i32 s25, s24, 31
	s_lshl_b64 s[24:25], s[24:25], 11
	s_add_u32 s24, s16, s24
	s_addc_u32 s25, s17, s25
	s_lshl_b32 s27, s30, 7
	s_add_u32 s24, s24, s27
	s_addc_u32 s25, s25, 0
	v_lshlrev_b32_e32 v194, 1, v186
	v_mov_b32_e32 v195, v1
	v_lshl_add_u64 v[2:3], s[24:25], 0, v[194:195]
	v_mov_b32_e32 v191, v1
	v_lshl_add_u64 v[4:5], v[2:3], 0, v[190:191]
	global_load_dwordx4 v[98:101], v[4:5], off
	global_load_dwordx4 v[102:105], v[4:5], off offset:32
	global_load_dwordx4 v[106:109], v[4:5], off offset:64
	global_load_dwordx4 v[110:113], v[4:5], off offset:96
	s_lshl_b32 s27, s30, 2
	v_mov_b32_e32 v193, v1
	v_mov_b32_e32 v0, s27
	v_lshl_add_u64 v[2:3], v[2:3], 0, v[192:193]
	global_load_dword v16, v0, s[0:1]
	global_load_dwordx4 v[114:117], v[2:3], off
	global_load_dwordx4 v[118:121], v[2:3], off offset:32
	global_load_dwordx4 v[122:125], v[2:3], off offset:64
	global_load_dwordx4 v[126:129], v[2:3], off offset:96
	s_mul_i32 s42, s8, 0x12000
	s_mul_hi_i32 s43, s8, 0x12000
	s_mul_hi_i32 s44, s8, 0x104000
	s_mul_i32 s45, s8, 0x104000
	s_lshl_b32 s8, s8, 1
	s_add_i32 s8, s8, s76
	s_mul_i32 s30, s8, 0x44000
	v_add_u32_e32 v189, s31, v219
	s_mul_hi_i32 s31, s8, 0x44000
	s_add_u32 s30, s96, s30
	s_addc_u32 s31, s97, s31
	s_lshl_b32 s8, s8, 2
	s_or_b32 s8, s8, s35
	s_lshl_b32 s46, s35, 6
	s_mul_hi_i32 s35, s8, 0x11000
	s_mul_i32 s8, s8, 0x11000
	s_mul_i32 s47, s46, s34
	s_add_u32 s34, s74, s8
	s_mul_i32 s38, s26, 0x220
	s_addc_u32 s35, s75, s35
	s_mul_hi_i32 s39, s26, 0x220
	s_add_u32 s38, s18, s38
	s_addc_u32 s39, s19, s39
	s_add_u32 s8, s45, 0x240000
	s_addc_u32 s44, s44, 0
	s_lshl_b32 s45, s47, 1
	s_add_u32 s45, s20, s45
	s_addc_u32 s47, s21, 0
	s_add_i32 s48, s41, 0xc0
	s_max_i32 s51, s41, 0x80
	s_min_i32 s50, s48, s40
	s_addk_i32 s51, 0xff80
	s_and_b64 s[40:41], s[22:23], exec
	v_mov_b32_e32 v14, v1
	v_mov_b32_e32 v15, v1
	s_cselect_b32 s41, s44, s43
	s_cselect_b32 s40, s8, s42
	v_mov_b32_e32 v0, v1
	v_mov_b32_e32 v2, v1
	v_mov_b32_e32 v3, v1
	v_mov_b32_e32 v4, v1
	v_mov_b32_e32 v5, v1
	v_mov_b32_e32 v6, v1
	v_mov_b32_e32 v7, v1
	v_mov_b32_e32 v8, v1
	v_mov_b32_e32 v9, v1
	v_mov_b32_e32 v10, v1
	v_mov_b32_e32 v11, v1
	v_mov_b32_e32 v12, v1
	v_mov_b32_e32 v13, v1
	v_mov_b64_e32 v[64:65], v[14:15]
	v_mov_b64_e32 v[48:49], v[14:15]
	s_waitcnt lgkmcnt(0)
	v_mov_b64_e32 v[32:33], v[14:15]
	s_lshl_b64 s[40:41], s[40:41], 1
	v_mov_b64_e32 v[62:63], v[12:13]
	v_mov_b64_e32 v[60:61], v[10:11]
	v_mov_b64_e32 v[58:59], v[8:9]
	v_mov_b64_e32 v[56:57], v[6:7]
	v_mov_b64_e32 v[54:55], v[4:5]
	v_mov_b64_e32 v[52:53], v[2:3]
	v_mov_b64_e32 v[50:51], v[0:1]
	v_mov_b64_e32 v[46:47], v[12:13]
	v_mov_b64_e32 v[44:45], v[10:11]
	v_mov_b64_e32 v[42:43], v[8:9]
	v_mov_b64_e32 v[40:41], v[6:7]
	v_mov_b64_e32 v[38:39], v[4:5]
	v_mov_b64_e32 v[36:37], v[2:3]
	v_mov_b64_e32 v[34:35], v[0:1]
	v_mov_b64_e32 v[30:31], v[12:13]
	v_mov_b64_e32 v[28:29], v[10:11]
	v_mov_b64_e32 v[26:27], v[8:9]
	v_mov_b64_e32 v[24:25], v[6:7]
	v_mov_b64_e32 v[22:23], v[4:5]
	v_mov_b64_e32 v[20:21], v[2:3]
	v_mov_b64_e32 v[18:19], v[0:1]
	s_add_u32 s40, s45, s40
	s_waitcnt vmcnt(0)
	v_mul_f32_e32 v191, 0x3fb8aa3b, v16
	v_mov_b64_e32 v[16:17], v[14:15]
	s_mov_b64 s[26:27], -1
	v_mov_b32_e32 v220, v185
	s_addc_u32 s41, s47, s41
	s_lshl_b32 s52, s46, 1
	v_mov_b32_e32 v193, v185
	v_mov_b32_e32 v221, v191
	v_mov_b64_e32 v[14:15], v[12:13]
	v_mov_b64_e32 v[12:13], v[10:11]
	v_mov_b64_e32 v[10:11], v[8:9]
	v_mov_b64_e32 v[8:9], v[6:7]
	v_mov_b64_e32 v[6:7], v[4:5]
	v_mov_b64_e32 v[4:5], v[2:3]
	v_mov_b64_e32 v[2:3], v[0:1]
	s_branch .LBB0_837

.LBB0_843:
	s_waitcnt vmcnt(0)
	v_mfma_f32_32x32x16_bf16 v[82:97], v[150:153], v[98:101], 0
	s_mov_b32 s8, s44
	s_add_i32 s44, s44, 32
	s_cmp_ge_i32 s44, s53
	s_cselect_b64 s[46:47], -1, 0
	s_cmp_lt_i32 s44, s53
	v_mov_b64_e32 v[224:225], v[136:137]
	s_cselect_b32 s8, s44, s8
	v_mfma_f32_32x32x16_bf16 v[66:81], v[150:153], v[114:117], 0
	v_mov_b64_e32 v[222:223], v[134:135]
	v_lshl_add_u64 v[134:135], s[8:9], 1, v[196:197]
	v_mov_b32_e32 v201, v1
	v_lshl_add_u64 v[136:137], v[134:135], 0, v[0:1]
	v_lshl_add_u64 v[134:135], v[134:135], 0, v[200:201]
	global_load_dwordx4 v[162:165], v[136:137], off
	global_load_dwordx4 v[166:169], v[136:137], off offset:32
	global_load_dwordx4 v[170:173], v[134:135], off
	global_load_dwordx4 v[174:177], v[134:135], off offset:32
	v_mfma_f32_32x32x16_bf16 v[82:97], v[146:149], v[102:105], v[82:97]
	v_add_u32_e32 v134, s8, v181
	v_mad_u64_u32 v[134:135], s[48:49], v134, s91, v[198:199]
	s_andn2_b64 vcc, exec, s[42:43]
	v_mfma_f32_32x32x16_bf16 v[66:81], v[146:149], v[118:121], v[66:81]
	global_load_dwordx4 v[150:153], v[134:135], off
	global_load_dwordx4 v[146:149], v[134:135], off offset:32
	v_mfma_f32_32x32x16_bf16 v[82:97], v[142:145], v[106:109], v[82:97]
	v_mfma_f32_32x32x16_bf16 v[66:81], v[142:145], v[122:125], v[66:81]
	global_load_dwordx4 v[142:145], v[134:135], off offset:64
	s_nop 0
	global_load_dwordx4 v[134:137], v[134:135], off offset:96
	v_mfma_f32_32x32x16_bf16 v[82:97], v[222:225], v[110:113], v[82:97]
	v_mfma_f32_32x32x16_bf16 v[66:81], v[222:225], v[126:129], v[66:81]
	s_sub_i32 s101, s44, s100
	s_add_i32 s101, s101, 32
	s_cmp_le_u32 s101, 0xa0
	s_cbranch_scc1 .LBB0_845
	s_cbranch_vccnz .LBB0_845
	v_add_u32_e32 v201, 27, v195
	s_movk_i32 s8, 0xfeff
	v_cmp_gt_u32_e32 vcc, s8, v201
	v_add_u32_e32 v201, 26, v195
	s_nop 5
	v_cndmask_b32_e32 v82, v82, v205, vcc
	v_cmp_lt_u32_e32 vcc, s82, v201
	v_add_u32_e32 v201, 25, v195
	s_nop 0
	v_cndmask_b32_e32 v83, v205, v83, vcc
	v_cmp_lt_u32_e32 vcc, s82, v201
	v_add_u32_e32 v201, 24, v195
	s_nop 0
	v_cndmask_b32_e32 v84, v205, v84, vcc
	v_cmp_lt_u32_e32 vcc, s82, v201
	v_add_u32_e32 v201, 19, v195
	s_nop 0
	v_cndmask_b32_e32 v85, v205, v85, vcc
	v_cmp_lt_u32_e32 vcc, s82, v201
	v_add_u32_e32 v201, 18, v195
	s_nop 0
	v_cndmask_b32_e32 v86, v205, v86, vcc
	v_cmp_lt_u32_e32 vcc, s82, v201
	v_add_u32_e32 v201, 17, v195
	s_nop 0
	v_cndmask_b32_e32 v87, v205, v87, vcc
	v_cmp_lt_u32_e32 vcc, s82, v201
	v_add_u32_e32 v201, 16, v195
	s_nop 0
	v_cndmask_b32_e32 v88, v205, v88, vcc
	v_cmp_lt_u32_e32 vcc, s82, v201
	v_add_u32_e32 v201, 11, v195
	s_nop 0
	v_cndmask_b32_e32 v89, v205, v89, vcc
	v_cmp_lt_u32_e32 vcc, s82, v201
	v_add_u32_e32 v201, 10, v195
	s_nop 0
	v_cndmask_b32_e32 v90, v205, v90, vcc
	v_cmp_lt_u32_e32 vcc, s82, v201
	v_add_u32_e32 v201, 9, v195
	s_nop 0
	v_cndmask_b32_e32 v91, v205, v91, vcc
	v_cmp_lt_u32_e32 vcc, s82, v201
	v_add_u32_e32 v201, 8, v195
	s_nop 0
	v_cndmask_b32_e32 v92, v205, v92, vcc
	v_cmp_lt_u32_e32 vcc, s82, v201
	v_add_u32_e32 v201, 3, v195
	s_nop 0
	v_cndmask_b32_e32 v93, v205, v93, vcc
	v_cmp_lt_u32_e32 vcc, s82, v201
	v_add_u32_e32 v201, 2, v195
	s_nop 0
	v_cndmask_b32_e32 v94, v205, v94, vcc
	v_cmp_lt_u32_e32 vcc, s82, v201
	v_add_u32_e32 v201, 1, v195
	s_nop 0
	v_cndmask_b32_e32 v95, v205, v95, vcc
	v_cmp_lt_u32_e32 vcc, s82, v201
	v_add_u32_e32 v201, 59, v195
	s_nop 0
	v_cndmask_b32_e32 v96, v205, v96, vcc
	v_cmp_lt_u32_e32 vcc, s82, v195
	s_nop 1
	v_cndmask_b32_e32 v97, v205, v97, vcc
	v_cmp_lt_u32_e32 vcc, s82, v201
	v_add_u32_e32 v201, 58, v195
	s_nop 0
	v_cndmask_b32_e32 v66, v205, v66, vcc
	v_cmp_lt_u32_e32 vcc, s82, v201
	v_add_u32_e32 v201, 57, v195
	s_nop 0
	v_cndmask_b32_e32 v67, v205, v67, vcc
	v_cmp_lt_u32_e32 vcc, s82, v201
	v_add_u32_e32 v201, 56, v195
	s_nop 0
	v_cndmask_b32_e32 v68, v205, v68, vcc
	v_cmp_lt_u32_e32 vcc, s82, v201
	v_add_u32_e32 v201, 51, v195
	s_nop 0
	v_cndmask_b32_e32 v69, v205, v69, vcc
	v_cmp_lt_u32_e32 vcc, s82, v201
	v_add_u32_e32 v201, 50, v195
	s_nop 0
	v_cndmask_b32_e32 v70, v205, v70, vcc
	v_cmp_lt_u32_e32 vcc, s82, v201
	v_add_u32_e32 v201, 49, v195
	s_nop 0
	v_cndmask_b32_e32 v71, v205, v71, vcc
	v_cmp_lt_u32_e32 vcc, s82, v201
	v_add_u32_e32 v201, 48, v195
	s_nop 0
	v_cndmask_b32_e32 v72, v205, v72, vcc
	v_cmp_lt_u32_e32 vcc, s82, v201
	v_add_u32_e32 v201, 43, v195
	s_nop 0
	v_cndmask_b32_e32 v73, v205, v73, vcc
	v_cmp_lt_u32_e32 vcc, s82, v201
	v_add_u32_e32 v201, 42, v195
	s_nop 0
	v_cndmask_b32_e32 v74, v205, v74, vcc
	v_cmp_lt_u32_e32 vcc, s82, v201
	v_add_u32_e32 v201, 41, v195
	s_nop 0
	v_cndmask_b32_e32 v75, v205, v75, vcc
	v_cmp_lt_u32_e32 vcc, s82, v201
	v_add_u32_e32 v201, 40, v195
	s_nop 0
	v_cndmask_b32_e32 v76, v205, v76, vcc
	v_cmp_lt_u32_e32 vcc, s82, v201
	v_add_u32_e32 v201, 35, v195
	s_nop 0
	v_cndmask_b32_e32 v77, v205, v77, vcc
	v_cmp_lt_u32_e32 vcc, s82, v201
	v_add_u32_e32 v201, 34, v195
	s_nop 0
	v_cndmask_b32_e32 v78, v205, v78, vcc
	v_cmp_lt_u32_e32 vcc, s82, v201
	v_add_u32_e32 v201, 33, v195
	s_nop 0
	v_cndmask_b32_e32 v79, v205, v79, vcc
	v_cmp_lt_u32_e32 vcc, s82, v201
	v_add_u32_e32 v201, 32, v195
	s_nop 0
	v_cndmask_b32_e32 v80, v205, v80, vcc
	v_cmp_lt_u32_e32 vcc, s82, v201
	s_nop 1
	v_cndmask_b32_e32 v81, v205, v81, vcc

	.amdhsa_kernel _Z8mega_fwd4Args
		.amdhsa_group_segment_fixed_size 0
		.amdhsa_private_segment_fixed_size 0
		.amdhsa_kernarg_size 456
		.amdhsa_user_sgpr_count 2
		.amdhsa_user_sgpr_dispatch_ptr 0
		.amdhsa_user_sgpr_queue_ptr 0
		.amdhsa_user_sgpr_kernarg_segment_ptr 1
		.amdhsa_user_sgpr_dispatch_id 0
		.amdhsa_user_sgpr_kernarg_preload_length 0
		.amdhsa_user_sgpr_kernarg_preload_offset 0
		.amdhsa_user_sgpr_private_segment_size 0
		.amdhsa_uses_dynamic_stack 0
		.amdhsa_enable_private_segment 0
		.amdhsa_system_sgpr_workgroup_id_x 1
		.amdhsa_system_sgpr_workgroup_id_y 0
		.amdhsa_system_sgpr_workgroup_id_z 0
		.amdhsa_system_sgpr_workgroup_info 0
		.amdhsa_system_vgpr_workitem_id 2
		.amdhsa_next_free_vgpr 256
		.amdhsa_next_free_sgpr 102
		.amdhsa_accum_offset 256
		.amdhsa_reserve_vcc 1
		.amdhsa_float_round_mode_32 0
		.amdhsa_float_round_mode_16_64 0
		.amdhsa_float_denorm_mode_32 3
		.amdhsa_float_denorm_mode_16_64 3
		.amdhsa_dx10_clamp 1
		.amdhsa_ieee_mode 1
		.amdhsa_fp16_overflow 0
		.amdhsa_tg_split 0
		.amdhsa_exception_fp_ieee_invalid_op 0
		.amdhsa_exception_fp_denorm_src 0
		.amdhsa_exception_fp_ieee_div_zero 0
		.amdhsa_exception_fp_ieee_overflow 0
		.amdhsa_exception_fp_ieee_underflow 0
		.amdhsa_exception_fp_ieee_inexact 0
		.amdhsa_exception_int_div_zero 0
	.end_amdhsa_kernel

amdhsa.kernels:
  - .agpr_count:     0
    .args:
      - .offset:         0
        .size:           200
        .value_kind:     by_value
      - .offset:         200
        .size:           4
        .value_kind:     hidden_block_count_x
      - .offset:         204
        .size:           4
        .value_kind:     hidden_block_count_y
      - .offset:         208
        .size:           4
        .value_kind:     hidden_block_count_z
      - .offset:         212
        .size:           2
        .value_kind:     hidden_group_size_x
      - .offset:         214
        .size:           2
        .value_kind:     hidden_group_size_y
      - .offset:         216
        .size:           2
        .value_kind:     hidden_group_size_z
      - .offset:         218
        .size:           2
        .value_kind:     hidden_remainder_x
      - .offset:         220
        .size:           2
        .value_kind:     hidden_remainder_y
      - .offset:         222
        .size:           2
        .value_kind:     hidden_remainder_z
      - .offset:         240
        .size:           8
        .value_kind:     hidden_global_offset_x
      - .offset:         248
        .size:           8
        .value_kind:     hidden_global_offset_y
      - .offset:         256
        .size:           8
        .value_kind:     hidden_global_offset_z
      - .offset:         264
        .size:           2
        .value_kind:     hidden_grid_dims
      - .offset:         288
        .size:           8
        .value_kind:     hidden_multigrid_sync_arg
      - .offset:         320
        .size:           4
        .value_kind:     hidden_dynamic_lds_size
    .group_segment_fixed_size: 0
    .kernarg_segment_align: 8
    .kernarg_segment_size: 456
    .language:       OpenCL C
    .language_version:
      - 2
      - 0
    .max_flat_workgroup_size: 512
    .name:           _Z8mega_fwd4Args
    .private_segment_fixed_size: 0
    .sgpr_count:     108
    .sgpr_spill_count: 332
    .symbol:         _Z8mega_fwd4Args.kd
    .uniform_work_group_size: 1
    .uses_dynamic_stack: false
    .vgpr_count:     256
    .vgpr_spill_count: 0
    .wavefront_size: 64
